# grid barrier: non-last arrivers poll the top-level generation word directly instead of the per-XCD generation (one polling stage instead of two); release/acquire fences unchanged
# speedup vs baseline: 1.0115x; 1.0031x over previous
; DI unsigned xb_ld(unsigned* p) { return __hip_atomic_load(p, __ATOMIC_RELAXED, __HIP_MEMORY_SCOPE_AGENT); }
; DI unsigned xb_add(unsigned* p, unsigned v) { return __hip_atomic_fetch_add(p, v, __ATOMIC_RELAXED, __HIP_MEMORY_SCOPE_AGENT); }
; #define XB_SPIN(cond, bar) do { unsigned _sp = 0; while (cond) { __builtin_amdgcn_s_sleep(1); \
;     if ((++_sp & 255u) == 0u) { if (xb_ld(&(bar)[XB_TMO])) break; if (_sp > XB_SPIN_CAP) { atomicAdd(&(bar)[XB_TMO], 1u); break; } } } } while (0)
; DI void xcd_barrier(const XcdBarrier& b) {
;     ...
;     const unsigned old = xb_add(&bar[XB_XSUB(b.x)], 1u);
;     const unsigned gen = old / nloc;
;     if (old + 1u == (gen + 1u) * nloc) {
;       __builtin_amdgcn_fence(__ATOMIC_RELEASE, "agent");
;       asm volatile("s_waitcnt vmcnt(0)" ::: "memory");
;       const unsigned og = xb_add(&bar[XB_TOP], 1u);
;       const unsigned tg = og / nx;
;       if (og + 1u == (tg + 1u) * nx) xb_add(&bar[XB_TOPGEN], 1u);
;       else XB_SPIN(xb_ld(&bar[XB_TOPGEN]) == tg, bar);
;       __builtin_amdgcn_fence(__ATOMIC_ACQUIRE, "agent");
;       xb_add(&bar[XB_XGEN(b.x)], 1u);
;       asm volatile("s_waitcnt vmcnt(0)" ::: "memory");
;     } else {
;       XB_SPIN(xb_ld(&bar[XB_XGEN(b.x)]) == gen, bar);
;       __builtin_amdgcn_fence(__ATOMIC_ACQUIRE, "agent");
;       asm volatile("s_waitcnt vmcnt(0)" ::: "memory");
;     }
.LBB0_72:
	s_or_b64 exec, exec, s[4:5]
	v_cvt_f32_u32_e32 v4, v2
	s_waitcnt vmcnt(0)
	v_readfirstlane_b32 s3, v3
	v_rcp_iflag_f32_e32 v4, v4
	s_nop 0
	v_add_u32_e32 v1, s3, v1
	v_add_u32_e32 v5, 1, v1
	v_mul_f32_e32 v3, 0x4f7ffffe, v4
	v_cvt_u32_f32_e32 v3, v3
	v_sub_u32_e32 v4, 0, v2
	v_mul_lo_u32 v4, v4, v3
	v_mul_hi_u32 v4, v3, v4
	v_add_u32_e32 v3, v3, v4
	v_mul_hi_u32 v3, v1, v3
	v_mul_lo_u32 v4, v3, v2
	v_sub_u32_e32 v1, v1, v4
	v_add_u32_e32 v6, 1, v3
	v_cmp_ge_u32_e32 vcc, v1, v2
	v_sub_u32_e32 v4, v1, v2
	s_nop 0
	v_cndmask_b32_e32 v3, v3, v6, vcc
	v_cndmask_b32_e32 v1, v1, v4, vcc
	v_add_u32_e32 v4, 1, v3
	v_cmp_ge_u32_e32 vcc, v1, v2
	s_nop 1
	v_cndmask_b32_e32 v1, v3, v4, vcc
	v_mad_u64_u32 v[2:3], s[4:5], v2, v1, v[2:3]
	v_cmp_ne_u32_e32 vcc, v5, v2
	s_and_saveexec_b64 s[4:5], vcc
	s_xor_b64 s[4:5], exec, s[4:5]
	s_cbranch_execz .LBB0_86
	v_readlane_b32 s6, v251, 57
	s_waitcnt lgkmcnt(0)
	v_mov_b32_e32 v0, 0
	v_readlane_b32 s7, v251, 58
	s_nop 4
	global_load_dword v2, v0, s[6:7] sc1
	s_waitcnt vmcnt(0)
	v_cmp_eq_u32_e32 vcc, v2, v1
	s_and_saveexec_b64 s[6:7], vcc
	s_cbranch_execz .LBB0_85
	s_mov_b32 s3, 1
	s_mov_b64 s[8:9], 0
	s_branch .LBB0_76

; DI unsigned xb_ld(unsigned* p) { return __hip_atomic_load(p, __ATOMIC_RELAXED, __HIP_MEMORY_SCOPE_AGENT); }
; #define XB_SPIN(cond, bar) do { unsigned _sp = 0; while (cond) { __builtin_amdgcn_s_sleep(1); \
;     if ((++_sp & 255u) == 0u) { if (xb_ld(&(bar)[XB_TMO])) break; if (_sp > XB_SPIN_CAP) { atomicAdd(&(bar)[XB_TMO], 1u); break; } } } } while (0)
; DI void xcd_barrier(const XcdBarrier& b) {
;     ...
;       XB_SPIN(xb_ld(&bar[XB_XGEN(b.x)]) == gen, bar);
.LBB0_78:
	v_readlane_b32 s12, v251, 57
	v_readlane_b32 s13, v251, 58
	s_add_i32 s3, s3, 1
	s_mov_b64 s[14:15], -1
	s_nop 2
	global_load_dword v2, v0, s[12:13] sc1
	s_waitcnt vmcnt(0)
	v_cmp_ne_u32_e32 vcc, v2, v1
	s_orn2_b64 s[12:13], vcc, exec
	s_branch .LBB0_75

; DI unsigned xb_ld(unsigned* p) { return __hip_atomic_load(p, __ATOMIC_RELAXED, __HIP_MEMORY_SCOPE_AGENT); }
; DI unsigned xb_add(unsigned* p, unsigned v) { return __hip_atomic_fetch_add(p, v, __ATOMIC_RELAXED, __HIP_MEMORY_SCOPE_AGENT); }
; #define XB_SPIN(cond, bar) do { unsigned _sp = 0; while (cond) { __builtin_amdgcn_s_sleep(1); \
;     if ((++_sp & 255u) == 0u) { if (xb_ld(&(bar)[XB_TMO])) break; if (_sp > XB_SPIN_CAP) { atomicAdd(&(bar)[XB_TMO], 1u); break; } } } } while (0)
; DI void xcd_barrier(const XcdBarrier& b) {
;     ...
;     const unsigned old = xb_add(&bar[XB_XSUB(b.x)], 1u);
;     const unsigned gen = old / nloc;
;     if (old + 1u == (gen + 1u) * nloc) {
;       __builtin_amdgcn_fence(__ATOMIC_RELEASE, "agent");
;       asm volatile("s_waitcnt vmcnt(0)" ::: "memory");
;       const unsigned og = xb_add(&bar[XB_TOP], 1u);
;       const unsigned tg = og / nx;
;       if (og + 1u == (tg + 1u) * nx) xb_add(&bar[XB_TOPGEN], 1u);
;       else XB_SPIN(xb_ld(&bar[XB_TOPGEN]) == tg, bar);
;       __builtin_amdgcn_fence(__ATOMIC_ACQUIRE, "agent");
;       xb_add(&bar[XB_XGEN(b.x)], 1u);
;       asm volatile("s_waitcnt vmcnt(0)" ::: "memory");
;     } else {
;       XB_SPIN(xb_ld(&bar[XB_XGEN(b.x)]) == gen, bar);
;       __builtin_amdgcn_fence(__ATOMIC_ACQUIRE, "agent");
;       asm volatile("s_waitcnt vmcnt(0)" ::: "memory");
;     }
.LBB0_159:
	s_or_b64 exec, exec, s[2:3]
	s_waitcnt vmcnt(0)
	v_readfirstlane_b32 s2, v4
	v_sub_u32_e32 v5, 0, v2
	s_nop 0
	v_add_u32_e32 v4, s2, v3
	v_cvt_f32_u32_e32 v3, v2
	v_rcp_iflag_f32_e32 v3, v3
	s_nop 0
	v_mul_f32_e32 v3, 0x4f7ffffe, v3
	v_cvt_u32_f32_e32 v3, v3
	v_mul_lo_u32 v5, v5, v3
	v_mul_hi_u32 v5, v3, v5
	v_add_u32_e32 v3, v3, v5
	v_mul_hi_u32 v3, v4, v3
	v_mul_lo_u32 v5, v3, v2
	v_sub_u32_e32 v5, v4, v5
	v_cmp_ge_u32_e32 vcc, v5, v2
	v_add_u32_e32 v6, 1, v3
	s_nop 0
	v_cndmask_b32_e32 v3, v3, v6, vcc
	v_sub_u32_e32 v6, v5, v2
	v_cndmask_b32_e32 v5, v5, v6, vcc
	v_cmp_ge_u32_e32 vcc, v5, v2
	v_add_u32_e32 v5, 1, v3
	v_add_u32_e32 v6, 1, v4
	v_cndmask_b32_e32 v3, v3, v5, vcc
	v_mad_u64_u32 v[4:5], s[2:3], v2, v3, v[2:3]
	v_cmp_ne_u32_e32 vcc, v6, v4
	s_and_saveexec_b64 s[2:3], vcc
	s_xor_b64 s[2:3], exec, s[2:3]
	s_cbranch_execz .LBB0_173
	v_readlane_b32 s4, v251, 57
	v_readlane_b32 s5, v251, 58
	s_waitcnt lgkmcnt(0)
	s_nop 3
	global_load_dword v0, v1, s[4:5] sc1
	s_waitcnt vmcnt(0)
	v_cmp_eq_u32_e32 vcc, v0, v3
	s_and_saveexec_b64 s[4:5], vcc
	s_cbranch_execz .LBB0_172
	s_mov_b32 s38, 1
	s_mov_b64 s[6:7], 0
	s_branch .LBB0_163

; DI unsigned xb_ld(unsigned* p) { return __hip_atomic_load(p, __ATOMIC_RELAXED, __HIP_MEMORY_SCOPE_AGENT); }
; #define XB_SPIN(cond, bar) do { unsigned _sp = 0; while (cond) { __builtin_amdgcn_s_sleep(1); \
;     if ((++_sp & 255u) == 0u) { if (xb_ld(&(bar)[XB_TMO])) break; if (_sp > XB_SPIN_CAP) { atomicAdd(&(bar)[XB_TMO], 1u); break; } } } } while (0)
; DI void xcd_barrier(const XcdBarrier& b) {
;     ...
;       XB_SPIN(xb_ld(&bar[XB_XGEN(b.x)]) == gen, bar);
.LBB0_165:
	v_readlane_b32 s12, v251, 57
	v_readlane_b32 s13, v251, 58
	s_add_i32 s38, s38, 1
	s_mov_b64 s[20:21], -1
	s_nop 2
	global_load_dword v0, v1, s[12:13] sc1
	s_waitcnt vmcnt(0)
	v_cmp_ne_u32_e32 vcc, v0, v3
	s_orn2_b64 s[18:19], vcc, exec
	s_branch .LBB0_162

; DI unsigned xb_ld(unsigned* p) { return __hip_atomic_load(p, __ATOMIC_RELAXED, __HIP_MEMORY_SCOPE_AGENT); }
; DI unsigned xb_add(unsigned* p, unsigned v) { return __hip_atomic_fetch_add(p, v, __ATOMIC_RELAXED, __HIP_MEMORY_SCOPE_AGENT); }
; #define XB_SPIN(cond, bar) do { unsigned _sp = 0; while (cond) { __builtin_amdgcn_s_sleep(1); \
;     if ((++_sp & 255u) == 0u) { if (xb_ld(&(bar)[XB_TMO])) break; if (_sp > XB_SPIN_CAP) { atomicAdd(&(bar)[XB_TMO], 1u); break; } } } } while (0)
; DI void xcd_barrier(const XcdBarrier& b) {
;     ...
;     const unsigned old = xb_add(&bar[XB_XSUB(b.x)], 1u);
;     const unsigned gen = old / nloc;
;     if (old + 1u == (gen + 1u) * nloc) {
;       __builtin_amdgcn_fence(__ATOMIC_RELEASE, "agent");
;       asm volatile("s_waitcnt vmcnt(0)" ::: "memory");
;       const unsigned og = xb_add(&bar[XB_TOP], 1u);
;       const unsigned tg = og / nx;
;       if (og + 1u == (tg + 1u) * nx) xb_add(&bar[XB_TOPGEN], 1u);
;       else XB_SPIN(xb_ld(&bar[XB_TOPGEN]) == tg, bar);
;       __builtin_amdgcn_fence(__ATOMIC_ACQUIRE, "agent");
;       xb_add(&bar[XB_XGEN(b.x)], 1u);
;       asm volatile("s_waitcnt vmcnt(0)" ::: "memory");
;     } else {
;       XB_SPIN(xb_ld(&bar[XB_XGEN(b.x)]) == gen, bar);
;       __builtin_amdgcn_fence(__ATOMIC_ACQUIRE, "agent");
;       asm volatile("s_waitcnt vmcnt(0)" ::: "memory");
;     }
.LBB0_358:
	s_or_b64 exec, exec, s[2:3]
	s_waitcnt vmcnt(0)
	v_readfirstlane_b32 s2, v4
	v_sub_u32_e32 v5, 0, v2
	s_nop 0
	v_add_u32_e32 v4, s2, v3
	v_cvt_f32_u32_e32 v3, v2
	v_rcp_iflag_f32_e32 v3, v3
	s_nop 0
	v_mul_f32_e32 v3, 0x4f7ffffe, v3
	v_cvt_u32_f32_e32 v3, v3
	v_mul_lo_u32 v5, v5, v3
	v_mul_hi_u32 v5, v3, v5
	v_add_u32_e32 v3, v3, v5
	v_mul_hi_u32 v3, v4, v3
	v_mul_lo_u32 v5, v3, v2
	v_sub_u32_e32 v5, v4, v5
	v_cmp_ge_u32_e32 vcc, v5, v2
	v_add_u32_e32 v6, 1, v3
	s_nop 0
	v_cndmask_b32_e32 v3, v3, v6, vcc
	v_sub_u32_e32 v6, v5, v2
	v_cndmask_b32_e32 v5, v5, v6, vcc
	v_cmp_ge_u32_e32 vcc, v5, v2
	v_add_u32_e32 v5, 1, v3
	v_add_u32_e32 v6, 1, v4
	v_cndmask_b32_e32 v3, v3, v5, vcc
	v_mad_u64_u32 v[4:5], s[2:3], v2, v3, v[2:3]
	v_cmp_ne_u32_e32 vcc, v6, v4
	s_and_saveexec_b64 s[2:3], vcc
	s_xor_b64 s[2:3], exec, s[2:3]
	s_cbranch_execz .LBB0_372
	v_readlane_b32 s4, v251, 57
	v_readlane_b32 s5, v251, 58
	s_waitcnt lgkmcnt(0)
	s_nop 3
	global_load_dword v0, v1, s[4:5] sc1
	s_waitcnt vmcnt(0)
	v_cmp_eq_u32_e32 vcc, v0, v3
	s_and_saveexec_b64 s[4:5], vcc
	s_cbranch_execz .LBB0_371
	s_mov_b32 s40, 1
	s_mov_b64 s[6:7], 0
	s_branch .LBB0_362

; DI unsigned xb_ld(unsigned* p) { return __hip_atomic_load(p, __ATOMIC_RELAXED, __HIP_MEMORY_SCOPE_AGENT); }
; #define XB_SPIN(cond, bar) do { unsigned _sp = 0; while (cond) { __builtin_amdgcn_s_sleep(1); \
;     if ((++_sp & 255u) == 0u) { if (xb_ld(&(bar)[XB_TMO])) break; if (_sp > XB_SPIN_CAP) { atomicAdd(&(bar)[XB_TMO], 1u); break; } } } } while (0)
; DI void xcd_barrier(const XcdBarrier& b) {
;     ...
;       XB_SPIN(xb_ld(&bar[XB_XGEN(b.x)]) == gen, bar);
.LBB0_364:
	v_readlane_b32 s18, v251, 57
	v_readlane_b32 s19, v251, 58
	s_add_i32 s40, s40, 1
	s_mov_b64 s[36:37], -1
	s_nop 2
	global_load_dword v0, v1, s[18:19] sc1
	s_waitcnt vmcnt(0)
	v_cmp_ne_u32_e32 vcc, v0, v3
	s_orn2_b64 s[18:19], vcc, exec
	s_branch .LBB0_361

; DI unsigned xb_ld(unsigned* p) { return __hip_atomic_load(p, __ATOMIC_RELAXED, __HIP_MEMORY_SCOPE_AGENT); }
; #define XB_SPIN(cond, bar) do { unsigned _sp = 0; while (cond) { __builtin_amdgcn_s_sleep(1); \
;     if ((++_sp & 255u) == 0u) { if (xb_ld(&(bar)[XB_TMO])) break; if (_sp > XB_SPIN_CAP) { atomicAdd(&(bar)[XB_TMO], 1u); break; } } } } while (0)
; DI void xcd_barrier(const XcdBarrier& b) {
;     ...
;       XB_SPIN(xb_ld(&bar[XB_XGEN(b.x)]) == gen, bar);
.LBB0_495:
	v_readlane_b32 s18, v251, 57
	v_readlane_b32 s19, v251, 58
	s_add_i32 s38, s38, 1
	s_mov_b64 s[34:35], -1
	s_nop 2
	global_load_dword v0, v1, s[18:19] sc1
	s_waitcnt vmcnt(0)
	v_cmp_ne_u32_e32 vcc, v0, v3
	s_orn2_b64 s[18:19], vcc, exec
	s_branch .LBB0_492
